# plus: tuned K-loop transplanted into generic plain GEMM (SGPR addressing, balanced DMA), swiglu epilogue rewritten with packed f32 ops and interleaved chains
# speedup vs baseline: 1.0028x; 1.0028x over previous
.LBB0_415:
	v_writelane_b32 v250, s5, 0
	v_writelane_b32 v250, s23, 1
	v_writelane_b32 v250, s26, 2
	v_writelane_b32 v250, s27, 3
	v_writelane_b32 v250, s28, 4
	v_writelane_b32 v250, s29, 5
	v_writelane_b32 v250, s42, 6
	v_writelane_b32 v250, s43, 7
	v_writelane_b32 v250, s44, 8
	v_writelane_b32 v250, s45, 9
	v_writelane_b32 v250, s46, 10
	v_writelane_b32 v250, s47, 11
	v_writelane_b32 v250, s48, 12
	v_writelane_b32 v250, s49, 13
	v_writelane_b32 v250, s50, 14
	v_writelane_b32 v250, s51, 15
	v_writelane_b32 v250, s53, 16
	v_writelane_b32 v250, s54, 17
	v_writelane_b32 v250, s55, 18
	v_writelane_b32 v250, s56, 19
	v_writelane_b32 v250, s57, 20
	v_writelane_b32 v250, s58, 21
	v_writelane_b32 v250, s59, 22
	v_writelane_b32 v250, s60, 23
	v_writelane_b32 v250, s61, 24
	v_writelane_b32 v250, s63, 25
	v_writelane_b32 v250, s64, 26
	v_writelane_b32 v250, s65, 27
	s_add_i32 s53, s90, 0x80
	s_add_i32 s54, s52, -4
	s_add_i32 s55, s52, -3
	s_mov_b32 s56, s48
	s_add_i32 s57, s56, 0x2000
	s_add_i32 s58, s56, 0x4000
	s_add_i32 s59, s56, 0x6000
	s_add_i32 s60, s56, 0x8000
	s_add_i32 s61, s56, 0xa000
	v_readfirstlane_b32 s42, v6
	v_readfirstlane_b32 s43, v7
	v_readfirstlane_b32 s28, v4
	v_readfirstlane_b32 s29, v5
	v_readfirstlane_b32 s26, v146
	v_readfirstlane_b32 s5, v147
	v_readfirstlane_b32 s27, v148
	v_readfirstlane_b32 s23, v149
	s_add_u32 s28, s28, 0x100
	s_addc_u32 s29, s29, 0
	s_mov_b32 s63, -2
	v_mov_b32_e32 v4, 0
	v_mov_b32_e32 v5, v4
	v_mov_b32_e32 v6, v4
	v_mov_b32_e32 v7, v4
	v_mov_b32_e32 v8, v4
	v_mov_b32_e32 v9, v4
	v_mov_b32_e32 v10, v4
	v_mov_b32_e32 v11, v4
	v_mov_b32_e32 v20, v4
	v_mov_b32_e32 v21, v4
	v_mov_b32_e32 v22, v4
	v_mov_b32_e32 v23, v4
	v_mov_b32_e32 v24, v4
	v_mov_b32_e32 v25, v4
	v_mov_b32_e32 v26, v4
	v_mov_b32_e32 v27, v4
	v_mov_b32_e32 v36, v4
	v_mov_b32_e32 v37, v4
	v_mov_b32_e32 v38, v4
	v_mov_b32_e32 v39, v4
	v_mov_b32_e32 v40, v4
	v_mov_b32_e32 v41, v4
	v_mov_b32_e32 v42, v4
	v_mov_b32_e32 v43, v4
	v_mov_b32_e32 v52, v4
	v_mov_b32_e32 v53, v4
	v_mov_b32_e32 v54, v4
	v_mov_b32_e32 v55, v4
	v_mov_b32_e32 v56, v4
	v_mov_b32_e32 v57, v4
	v_mov_b32_e32 v58, v4
	v_mov_b32_e32 v59, v4
	v_mov_b32_e32 v12, v4
	v_mov_b32_e32 v13, v4
	v_mov_b32_e32 v14, v4
	v_mov_b32_e32 v15, v4
	v_mov_b32_e32 v16, v4
	v_mov_b32_e32 v17, v4
	v_mov_b32_e32 v18, v4
	v_mov_b32_e32 v19, v4
	v_mov_b32_e32 v28, v4
	v_mov_b32_e32 v29, v4
	v_mov_b32_e32 v30, v4
	v_mov_b32_e32 v31, v4
	v_mov_b32_e32 v32, v4
	v_mov_b32_e32 v33, v4
	v_mov_b32_e32 v34, v4
	v_mov_b32_e32 v35, v4
	v_mov_b32_e32 v44, v4
	v_mov_b32_e32 v45, v4
	v_mov_b32_e32 v46, v4
	v_mov_b32_e32 v47, v4
	v_mov_b32_e32 v48, v4
	v_mov_b32_e32 v49, v4
	v_mov_b32_e32 v50, v4
	v_mov_b32_e32 v51, v4
	v_mov_b32_e32 v60, v4
	v_mov_b32_e32 v61, v4
	v_mov_b32_e32 v62, v4
	v_mov_b32_e32 v63, v4
	v_mov_b32_e32 v64, v4
	v_mov_b32_e32 v65, v4
	v_mov_b32_e32 v66, v4
	v_mov_b32_e32 v67, v4
	v_mov_b32_e32 v68, v4
	v_mov_b32_e32 v69, v4
	v_mov_b32_e32 v70, v4
	v_mov_b32_e32 v71, v4
	v_mov_b32_e32 v72, v4
	v_mov_b32_e32 v73, v4
	v_mov_b32_e32 v74, v4
	v_mov_b32_e32 v75, v4
	v_mov_b32_e32 v84, v4
	v_mov_b32_e32 v85, v4
	v_mov_b32_e32 v86, v4
	v_mov_b32_e32 v87, v4
	v_mov_b32_e32 v88, v4
	v_mov_b32_e32 v89, v4
	v_mov_b32_e32 v90, v4
	v_mov_b32_e32 v91, v4
	v_mov_b32_e32 v100, v4
	v_mov_b32_e32 v101, v4
	v_mov_b32_e32 v102, v4
	v_mov_b32_e32 v103, v4
	v_mov_b32_e32 v104, v4
	v_mov_b32_e32 v105, v4
	v_mov_b32_e32 v106, v4
	v_mov_b32_e32 v107, v4
	v_mov_b32_e32 v116, v4
	v_mov_b32_e32 v117, v4
	v_mov_b32_e32 v118, v4
	v_mov_b32_e32 v119, v4
	v_mov_b32_e32 v120, v4
	v_mov_b32_e32 v121, v4
	v_mov_b32_e32 v122, v4
	v_mov_b32_e32 v123, v4
	v_mov_b32_e32 v76, v4
	v_mov_b32_e32 v77, v4
	v_mov_b32_e32 v78, v4
	v_mov_b32_e32 v79, v4
	v_mov_b32_e32 v80, v4
	v_mov_b32_e32 v81, v4
	v_mov_b32_e32 v82, v4
	v_mov_b32_e32 v83, v4
	v_mov_b32_e32 v92, v4
	v_mov_b32_e32 v93, v4
	v_mov_b32_e32 v94, v4
	v_mov_b32_e32 v95, v4
	v_mov_b32_e32 v96, v4
	v_mov_b32_e32 v97, v4
	v_mov_b32_e32 v98, v4
	v_mov_b32_e32 v99, v4
	v_mov_b32_e32 v108, v4
	v_mov_b32_e32 v109, v4
	v_mov_b32_e32 v110, v4
	v_mov_b32_e32 v111, v4
	v_mov_b32_e32 v112, v4
	v_mov_b32_e32 v113, v4
	v_mov_b32_e32 v114, v4
	v_mov_b32_e32 v115, v4
	v_mov_b32_e32 v124, v4
	v_mov_b32_e32 v125, v4
	v_mov_b32_e32 v126, v4
	v_mov_b32_e32 v127, v4
	v_mov_b32_e32 v128, v4
	v_mov_b32_e32 v129, v4
	v_mov_b32_e32 v130, v4
	v_mov_b32_e32 v131, v4
.Lg1_loop:
	s_add_u32 s44, s42, 0x100
	s_addc_u32 s45, s43, 0
	s_cmp_eq_u32 s63, s54
	s_cselect_b32 s50, s26, s44
	s_cselect_b32 s51, s5, s45
	s_cselect_b32 s48, s27, s28
	s_cselect_b32 s49, s23, s29
	s_add_i32 s64, 0, 0x10000
	v_add_u32_e32 v187, s64, v3
	s_add_i32 s65, 0, 0x14000
	ds_read_b128 v[164:167], v187
	ds_read_b128 v[168:171], v187 offset:1024
	ds_read_b128 v[188:191], v187 offset:2048
	ds_read_b128 v[192:195], v187 offset:3072
	v_add_u32_e32 v187, s65, v3
	ds_read_b128 v[196:199], v187
	ds_read_b128 v[200:203], v187 offset:1024
	ds_read_b128 v[204:207], v187 offset:2048
	ds_read_b128 v[208:211], v187 offset:3072
	s_add_u32 s46, s42, 0x80
	s_addc_u32 s47, s43, 0
	s_add_u32 s42, s42, s53
	s_addc_u32 s43, s43, 0
	s_mov_b32 m0, s60
	s_nop 0
	global_load_lds_dwordx4 v0, s[46:47]
	s_mov_b32 m0, s61
	s_nop 0
	global_load_lds_dwordx4 v142, s[46:47]
	s_add_i32 m0, s56, 0xc000
	s_nop 0
	global_load_lds_dwordx4 v0, s[42:43]
	s_add_i32 m0, s56, 0xe000
	s_nop 0
	global_load_lds_dwordx4 v142, s[42:43]
	ds_read_b128 v[212:215], v160
	ds_read_b128 v[216:219], v160 offset:1024
	ds_read_b128 v[220:223], v160 offset:2048
	ds_read_b128 v[224:227], v160 offset:3072
	ds_read_b128 v[228:231], v160 offset:4096
	ds_read_b128 v[232:235], v160 offset:5120
	ds_read_b128 v[236:239], v160 offset:6144
	ds_read_b128 v[240:243], v160 offset:7168
	s_waitcnt vmcnt(8)
	s_waitcnt lgkmcnt(0)
	s_barrier
	s_setprio 1
	s_waitcnt lgkmcnt(0)
	v_mfma_f32_16x16x32_bf16 v[128:131], v[164:167], v[212:215], v[128:131]
	v_mfma_f32_16x16x32_bf16 v[124:127], v[188:191], v[212:215], v[124:127]
	v_mfma_f32_16x16x32_bf16 v[112:115], v[164:167], v[220:223], v[112:115]
	v_mfma_f32_16x16x32_bf16 v[108:111], v[188:191], v[220:223], v[108:111]
	v_mfma_f32_16x16x32_bf16 v[96:99], v[164:167], v[228:231], v[96:99]
	v_mfma_f32_16x16x32_bf16 v[92:95], v[188:191], v[228:231], v[92:95]
	v_mfma_f32_16x16x32_bf16 v[80:83], v[164:167], v[236:239], v[80:83]
	v_mfma_f32_16x16x32_bf16 v[76:79], v[188:191], v[236:239], v[76:79]
	v_mfma_f32_16x16x32_bf16 v[128:131], v[168:171], v[216:219], v[128:131]
	v_mfma_f32_16x16x32_bf16 v[124:127], v[192:195], v[216:219], v[124:127]
	v_mfma_f32_16x16x32_bf16 v[112:115], v[168:171], v[224:227], v[112:115]
	v_mfma_f32_16x16x32_bf16 v[108:111], v[192:195], v[224:227], v[108:111]
	v_mfma_f32_16x16x32_bf16 v[96:99], v[168:171], v[232:235], v[96:99]
	v_mfma_f32_16x16x32_bf16 v[92:95], v[192:195], v[232:235], v[92:95]
	v_mfma_f32_16x16x32_bf16 v[80:83], v[168:171], v[240:243], v[80:83]
	v_mfma_f32_16x16x32_bf16 v[76:79], v[192:195], v[240:243], v[76:79]
	s_setprio 0
	s_setprio 1
	v_mfma_f32_16x16x32_bf16 v[120:123], v[196:199], v[212:215], v[120:123]
	v_mfma_f32_16x16x32_bf16 v[116:119], v[204:207], v[212:215], v[116:119]
	v_mfma_f32_16x16x32_bf16 v[104:107], v[196:199], v[220:223], v[104:107]
	v_mfma_f32_16x16x32_bf16 v[100:103], v[204:207], v[220:223], v[100:103]
	v_mfma_f32_16x16x32_bf16 v[88:91], v[196:199], v[228:231], v[88:91]
	v_mfma_f32_16x16x32_bf16 v[84:87], v[204:207], v[228:231], v[84:87]
	v_mfma_f32_16x16x32_bf16 v[72:75], v[196:199], v[236:239], v[72:75]
	v_mfma_f32_16x16x32_bf16 v[68:71], v[204:207], v[236:239], v[68:71]
	v_mfma_f32_16x16x32_bf16 v[120:123], v[200:203], v[216:219], v[120:123]
	v_mfma_f32_16x16x32_bf16 v[116:119], v[208:211], v[216:219], v[116:119]
	v_mfma_f32_16x16x32_bf16 v[104:107], v[200:203], v[224:227], v[104:107]
	v_mfma_f32_16x16x32_bf16 v[100:103], v[208:211], v[224:227], v[100:103]
	v_mfma_f32_16x16x32_bf16 v[88:91], v[200:203], v[232:235], v[88:91]
	v_mfma_f32_16x16x32_bf16 v[84:87], v[208:211], v[232:235], v[84:87]
	v_mfma_f32_16x16x32_bf16 v[72:75], v[200:203], v[240:243], v[72:75]
	v_mfma_f32_16x16x32_bf16 v[68:71], v[208:211], v[240:243], v[68:71]
	s_setprio 0
	s_barrier
	s_add_i32 s42, s64, s69
	s_mov_b32 m0, s42
	s_nop 0
	global_load_lds_dwordx4 v140, s[48:49]
	s_add_i32 m0, s42, 0x2000
	s_add_u32 s42, s48, s90
	s_addc_u32 s43, s49, 0
	s_add_i32 s64, s65, s69
	global_load_lds_dwordx4 v144, s[48:49]
	s_mov_b32 m0, s64
	s_nop 0
	global_load_lds_dwordx4 v140, s[42:43]
	s_add_i32 m0, s64, 0x2000
	s_nop 0
	global_load_lds_dwordx4 v144, s[42:43]
	ds_read_b128 v[212:215], v160 offset:16384
	ds_read_b128 v[216:219], v160 offset:17408
	ds_read_b128 v[220:223], v160 offset:18432
	ds_read_b128 v[224:227], v160 offset:19456
	ds_read_b128 v[228:231], v160 offset:20480
	ds_read_b128 v[232:235], v160 offset:21504
	ds_read_b128 v[236:239], v160 offset:22528
	ds_read_b128 v[240:243], v160 offset:23552
	s_waitcnt vmcnt(4)
	s_waitcnt lgkmcnt(0)
	s_barrier
	s_setprio 1
	s_waitcnt lgkmcnt(0)
	v_mfma_f32_16x16x32_bf16 v[64:67], v[164:167], v[212:215], v[64:67]
	v_mfma_f32_16x16x32_bf16 v[60:63], v[188:191], v[212:215], v[60:63]
	v_mfma_f32_16x16x32_bf16 v[48:51], v[164:167], v[220:223], v[48:51]
	v_mfma_f32_16x16x32_bf16 v[44:47], v[188:191], v[220:223], v[44:47]
	v_mfma_f32_16x16x32_bf16 v[32:35], v[164:167], v[228:231], v[32:35]
	v_mfma_f32_16x16x32_bf16 v[28:31], v[188:191], v[228:231], v[28:31]
	v_mfma_f32_16x16x32_bf16 v[16:19], v[164:167], v[236:239], v[16:19]
	v_mfma_f32_16x16x32_bf16 v[12:15], v[188:191], v[236:239], v[12:15]
	v_mfma_f32_16x16x32_bf16 v[64:67], v[168:171], v[216:219], v[64:67]
	v_mfma_f32_16x16x32_bf16 v[60:63], v[192:195], v[216:219], v[60:63]
	v_mfma_f32_16x16x32_bf16 v[48:51], v[168:171], v[224:227], v[48:51]
	v_mfma_f32_16x16x32_bf16 v[44:47], v[192:195], v[224:227], v[44:47]
	v_mfma_f32_16x16x32_bf16 v[32:35], v[168:171], v[232:235], v[32:35]
	v_mfma_f32_16x16x32_bf16 v[28:31], v[192:195], v[232:235], v[28:31]
	v_mfma_f32_16x16x32_bf16 v[16:19], v[168:171], v[240:243], v[16:19]
	v_mfma_f32_16x16x32_bf16 v[12:15], v[192:195], v[240:243], v[12:15]
	s_setprio 0
	s_setprio 1
	v_mfma_f32_16x16x32_bf16 v[56:59], v[196:199], v[212:215], v[56:59]
	v_mfma_f32_16x16x32_bf16 v[52:55], v[204:207], v[212:215], v[52:55]
	v_mfma_f32_16x16x32_bf16 v[40:43], v[196:199], v[220:223], v[40:43]
	v_mfma_f32_16x16x32_bf16 v[36:39], v[204:207], v[220:223], v[36:39]
	v_mfma_f32_16x16x32_bf16 v[24:27], v[196:199], v[228:231], v[24:27]
	v_mfma_f32_16x16x32_bf16 v[20:23], v[204:207], v[228:231], v[20:23]
	v_mfma_f32_16x16x32_bf16 v[8:11], v[196:199], v[236:239], v[8:11]
	v_mfma_f32_16x16x32_bf16 v[4:7], v[204:207], v[236:239], v[4:7]
	v_mfma_f32_16x16x32_bf16 v[56:59], v[200:203], v[216:219], v[56:59]
	v_mfma_f32_16x16x32_bf16 v[52:55], v[208:211], v[216:219], v[52:55]
	v_mfma_f32_16x16x32_bf16 v[40:43], v[200:203], v[224:227], v[40:43]
	v_mfma_f32_16x16x32_bf16 v[36:39], v[208:211], v[224:227], v[36:39]
	v_mfma_f32_16x16x32_bf16 v[24:27], v[200:203], v[232:235], v[24:27]
	v_mfma_f32_16x16x32_bf16 v[20:23], v[208:211], v[232:235], v[20:23]
	v_mfma_f32_16x16x32_bf16 v[8:11], v[200:203], v[240:243], v[8:11]
	v_mfma_f32_16x16x32_bf16 v[4:7], v[208:211], v[240:243], v[4:7]
	s_setprio 0
	s_barrier
	s_add_i32 s64, 0, 0x18000
	v_add_u32_e32 v187, s64, v3
	s_add_i32 s65, 0, 0x1c000
	ds_read_b128 v[164:167], v187
	ds_read_b128 v[168:171], v187 offset:1024
	ds_read_b128 v[188:191], v187 offset:2048
	ds_read_b128 v[192:195], v187 offset:3072
	v_add_u32_e32 v187, s65, v3
	ds_read_b128 v[196:199], v187
	ds_read_b128 v[200:203], v187 offset:1024
	ds_read_b128 v[204:207], v187 offset:2048
	ds_read_b128 v[208:211], v187 offset:3072
	s_add_u32 s42, s50, s90
	s_addc_u32 s43, s51, 0
	s_mov_b32 m0, s56
	s_nop 0
	global_load_lds_dwordx4 v0, s[50:51]
	s_mov_b32 m0, s57
	s_nop 0
	global_load_lds_dwordx4 v142, s[50:51]
	s_mov_b32 m0, s58
	s_nop 0
	global_load_lds_dwordx4 v0, s[42:43]
	s_mov_b32 m0, s59
	s_nop 0
	global_load_lds_dwordx4 v142, s[42:43]
	ds_read_b128 v[212:215], v160 offset:32768
	ds_read_b128 v[216:219], v160 offset:33792
	ds_read_b128 v[220:223], v160 offset:34816
	ds_read_b128 v[224:227], v160 offset:35840
	ds_read_b128 v[228:231], v160 offset:36864
	ds_read_b128 v[232:235], v160 offset:37888
	ds_read_b128 v[236:239], v160 offset:38912
	ds_read_b128 v[240:243], v160 offset:39936
	s_waitcnt vmcnt(8)
	s_waitcnt lgkmcnt(0)
	s_barrier
	s_setprio 1
	s_waitcnt lgkmcnt(0)
	v_mfma_f32_16x16x32_bf16 v[128:131], v[164:167], v[212:215], v[128:131]
	v_mfma_f32_16x16x32_bf16 v[124:127], v[188:191], v[212:215], v[124:127]
	v_mfma_f32_16x16x32_bf16 v[112:115], v[164:167], v[220:223], v[112:115]
	v_mfma_f32_16x16x32_bf16 v[108:111], v[188:191], v[220:223], v[108:111]
	v_mfma_f32_16x16x32_bf16 v[96:99], v[164:167], v[228:231], v[96:99]
	v_mfma_f32_16x16x32_bf16 v[92:95], v[188:191], v[228:231], v[92:95]
	v_mfma_f32_16x16x32_bf16 v[80:83], v[164:167], v[236:239], v[80:83]
	v_mfma_f32_16x16x32_bf16 v[76:79], v[188:191], v[236:239], v[76:79]
	v_mfma_f32_16x16x32_bf16 v[128:131], v[168:171], v[216:219], v[128:131]
	v_mfma_f32_16x16x32_bf16 v[124:127], v[192:195], v[216:219], v[124:127]
	v_mfma_f32_16x16x32_bf16 v[112:115], v[168:171], v[224:227], v[112:115]
	v_mfma_f32_16x16x32_bf16 v[108:111], v[192:195], v[224:227], v[108:111]
	v_mfma_f32_16x16x32_bf16 v[96:99], v[168:171], v[232:235], v[96:99]
	v_mfma_f32_16x16x32_bf16 v[92:95], v[192:195], v[232:235], v[92:95]
	v_mfma_f32_16x16x32_bf16 v[80:83], v[168:171], v[240:243], v[80:83]
	v_mfma_f32_16x16x32_bf16 v[76:79], v[192:195], v[240:243], v[76:79]
	s_setprio 0
	s_setprio 1
	v_mfma_f32_16x16x32_bf16 v[120:123], v[196:199], v[212:215], v[120:123]
	v_mfma_f32_16x16x32_bf16 v[116:119], v[204:207], v[212:215], v[116:119]
	v_mfma_f32_16x16x32_bf16 v[104:107], v[196:199], v[220:223], v[104:107]
	v_mfma_f32_16x16x32_bf16 v[100:103], v[204:207], v[220:223], v[100:103]
	v_mfma_f32_16x16x32_bf16 v[88:91], v[196:199], v[228:231], v[88:91]
	v_mfma_f32_16x16x32_bf16 v[84:87], v[204:207], v[228:231], v[84:87]
	v_mfma_f32_16x16x32_bf16 v[72:75], v[196:199], v[236:239], v[72:75]
	v_mfma_f32_16x16x32_bf16 v[68:71], v[204:207], v[236:239], v[68:71]
	v_mfma_f32_16x16x32_bf16 v[120:123], v[200:203], v[216:219], v[120:123]
	v_mfma_f32_16x16x32_bf16 v[116:119], v[208:211], v[216:219], v[116:119]
	v_mfma_f32_16x16x32_bf16 v[104:107], v[200:203], v[224:227], v[104:107]
	v_mfma_f32_16x16x32_bf16 v[100:103], v[208:211], v[224:227], v[100:103]
	v_mfma_f32_16x16x32_bf16 v[88:91], v[200:203], v[232:235], v[88:91]
	v_mfma_f32_16x16x32_bf16 v[84:87], v[208:211], v[232:235], v[84:87]
	v_mfma_f32_16x16x32_bf16 v[72:75], v[200:203], v[240:243], v[72:75]
	v_mfma_f32_16x16x32_bf16 v[68:71], v[208:211], v[240:243], v[68:71]
	s_setprio 0
	s_barrier
	s_add_u32 s42, s48, 0x80
	s_addc_u32 s43, s49, 0
	s_add_i32 s50, s64, s69
	s_mov_b32 m0, s50
	s_nop 0
	global_load_lds_dwordx4 v140, s[42:43]
	s_add_i32 m0, s50, 0x2000
	s_nop 0
	global_load_lds_dwordx4 v144, s[42:43]
	s_add_u32 s42, s48, s53
	s_addc_u32 s43, s49, 0
	s_add_i32 s48, s65, s69
	s_mov_b32 m0, s48
	s_nop 0
	global_load_lds_dwordx4 v140, s[42:43]
	s_add_i32 m0, s48, 0x2000
	s_nop 0
	global_load_lds_dwordx4 v144, s[42:43]
	ds_read_b128 v[212:215], v160 offset:49152
	ds_read_b128 v[216:219], v160 offset:50176
	ds_read_b128 v[220:223], v160 offset:51200
	ds_read_b128 v[224:227], v160 offset:52224
	ds_read_b128 v[228:231], v160 offset:53248
	ds_read_b128 v[232:235], v160 offset:54272
	ds_read_b128 v[236:239], v160 offset:55296
	ds_read_b128 v[240:243], v160 offset:56320
	s_waitcnt vmcnt(4)
	s_waitcnt lgkmcnt(0)
	s_barrier
	s_setprio 1
	s_waitcnt lgkmcnt(0)
	v_mfma_f32_16x16x32_bf16 v[64:67], v[164:167], v[212:215], v[64:67]
	v_mfma_f32_16x16x32_bf16 v[60:63], v[188:191], v[212:215], v[60:63]
	v_mfma_f32_16x16x32_bf16 v[48:51], v[164:167], v[220:223], v[48:51]
	v_mfma_f32_16x16x32_bf16 v[44:47], v[188:191], v[220:223], v[44:47]
	v_mfma_f32_16x16x32_bf16 v[32:35], v[164:167], v[228:231], v[32:35]
	v_mfma_f32_16x16x32_bf16 v[28:31], v[188:191], v[228:231], v[28:31]
	v_mfma_f32_16x16x32_bf16 v[16:19], v[164:167], v[236:239], v[16:19]
	v_mfma_f32_16x16x32_bf16 v[12:15], v[188:191], v[236:239], v[12:15]
	v_mfma_f32_16x16x32_bf16 v[64:67], v[168:171], v[216:219], v[64:67]
	v_mfma_f32_16x16x32_bf16 v[60:63], v[192:195], v[216:219], v[60:63]
	v_mfma_f32_16x16x32_bf16 v[48:51], v[168:171], v[224:227], v[48:51]
	v_mfma_f32_16x16x32_bf16 v[44:47], v[192:195], v[224:227], v[44:47]
	v_mfma_f32_16x16x32_bf16 v[32:35], v[168:171], v[232:235], v[32:35]
	v_mfma_f32_16x16x32_bf16 v[28:31], v[192:195], v[232:235], v[28:31]
	v_mfma_f32_16x16x32_bf16 v[16:19], v[168:171], v[240:243], v[16:19]
	v_mfma_f32_16x16x32_bf16 v[12:15], v[192:195], v[240:243], v[12:15]
	s_setprio 0
	s_setprio 1
	v_mfma_f32_16x16x32_bf16 v[56:59], v[196:199], v[212:215], v[56:59]
	v_mfma_f32_16x16x32_bf16 v[52:55], v[204:207], v[212:215], v[52:55]
	v_mfma_f32_16x16x32_bf16 v[40:43], v[196:199], v[220:223], v[40:43]
	v_mfma_f32_16x16x32_bf16 v[36:39], v[204:207], v[220:223], v[36:39]
	v_mfma_f32_16x16x32_bf16 v[24:27], v[196:199], v[228:231], v[24:27]
	v_mfma_f32_16x16x32_bf16 v[20:23], v[204:207], v[228:231], v[20:23]
	v_mfma_f32_16x16x32_bf16 v[8:11], v[196:199], v[236:239], v[8:11]
	v_mfma_f32_16x16x32_bf16 v[4:7], v[204:207], v[236:239], v[4:7]
	v_mfma_f32_16x16x32_bf16 v[56:59], v[200:203], v[216:219], v[56:59]
	v_mfma_f32_16x16x32_bf16 v[52:55], v[208:211], v[216:219], v[52:55]
	v_mfma_f32_16x16x32_bf16 v[40:43], v[200:203], v[224:227], v[40:43]
	v_mfma_f32_16x16x32_bf16 v[36:39], v[208:211], v[224:227], v[36:39]
	v_mfma_f32_16x16x32_bf16 v[24:27], v[200:203], v[232:235], v[24:27]
	v_mfma_f32_16x16x32_bf16 v[20:23], v[208:211], v[232:235], v[20:23]
	v_mfma_f32_16x16x32_bf16 v[8:11], v[200:203], v[240:243], v[8:11]
	v_mfma_f32_16x16x32_bf16 v[4:7], v[208:211], v[240:243], v[4:7]
	s_setprio 0
	s_barrier
	s_add_i32 s63, s63, 2
	s_add_u32 s28, s28, 0x100
	s_addc_u32 s29, s29, 0
	s_cmp_gt_u32 s63, s55
	s_mov_b64 s[42:43], s[44:45]
	s_cbranch_scc0 .Lg1_loop
	v_readlane_b32 s5, v250, 0
	v_readlane_b32 s23, v250, 1
	v_readlane_b32 s26, v250, 2
	v_readlane_b32 s27, v250, 3
	v_readlane_b32 s28, v250, 4
	v_readlane_b32 s29, v250, 5
	v_readlane_b32 s42, v250, 6
	v_readlane_b32 s43, v250, 7
	v_readlane_b32 s44, v250, 8
	v_readlane_b32 s45, v250, 9
	v_readlane_b32 s46, v250, 10
	v_readlane_b32 s47, v250, 11
	v_readlane_b32 s48, v250, 12
	v_readlane_b32 s49, v250, 13
	v_readlane_b32 s50, v250, 14
	v_readlane_b32 s51, v250, 15
	v_readlane_b32 s53, v250, 16
	v_readlane_b32 s54, v250, 17
	v_readlane_b32 s55, v250, 18
	v_readlane_b32 s56, v250, 19
	v_readlane_b32 s57, v250, 20
	v_readlane_b32 s58, v250, 21
	v_readlane_b32 s59, v250, 22
	v_readlane_b32 s60, v250, 23
	v_readlane_b32 s61, v250, 24
	v_readlane_b32 s63, v250, 25
	v_readlane_b32 s64, v250, 26
	v_readlane_b32 s65, v250, 27
	s_and_b64 vcc, exec, s[14:15]
	s_cbranch_vccz .LBB0_419
	s_barrier

.LBB0_500:
	s_add_u32 s44, s42, 0x100
	s_addc_u32 s45, s43, 0
	s_cmp_eq_u32 s63, 12
	s_cselect_b32 s50, s26, s44
	s_cselect_b32 s51, s5, s45
	s_cselect_b32 s48, s27, s28
	s_cselect_b32 s49, s23, s29
	s_add_i32 s64, 0, 0x10000
	v_add_u32_e32 v138, s64, v3
	s_add_i32 s65, 0, 0x14000
	ds_read_b128 v[146:149], v138
	ds_read_b128 v[150:153], v138 offset:1024
	ds_read_b128 v[154:157], v138 offset:2048
	ds_read_b128 v[158:161], v138 offset:3072
	v_add_u32_e32 v138, s65, v3
	ds_read_b128 v[162:165], v138
	ds_read_b128 v[166:169], v138 offset:1024
	ds_read_b128 v[170:173], v138 offset:2048
	ds_read_b128 v[186:189], v138 offset:3072
	s_add_u32 s46, s42, 0x80
	s_addc_u32 s47, s43, 0
	s_add_u32 s42, s42, 0x40080
	s_addc_u32 s43, s43, 0
	s_mov_b32 m0, s60
	s_nop 0
	global_load_lds_dwordx4 v144, s[46:47]
	s_mov_b32 m0, s61
	s_nop 0
	global_load_lds_dwordx4 v140, s[46:47]
	s_add_i32 m0, s56, 0xc000
	s_nop 0
	global_load_lds_dwordx4 v144, s[42:43]
	s_add_i32 m0, s56, 0xe000
	s_nop 0
	global_load_lds_dwordx4 v140, s[42:43]
	ds_read_b128 v[190:193], v132
	ds_read_b128 v[194:197], v132 offset:1024
	ds_read_b128 v[198:201], v132 offset:2048
	ds_read_b128 v[202:205], v132 offset:3072
	ds_read_b128 v[206:209], v132 offset:4096
	ds_read_b128 v[210:213], v132 offset:5120
	ds_read_b128 v[214:217], v132 offset:6144
	ds_read_b128 v[218:221], v132 offset:7168
	s_waitcnt vmcnt(8)
	s_waitcnt lgkmcnt(0)
	s_barrier
	s_setprio 1
	s_waitcnt lgkmcnt(0)
	v_mfma_f32_16x16x32_bf16 v[128:131], v[146:149], v[190:193], v[128:131]
	v_mfma_f32_16x16x32_bf16 v[124:127], v[154:157], v[190:193], v[124:127]
	v_mfma_f32_16x16x32_bf16 v[112:115], v[146:149], v[198:201], v[112:115]
	v_mfma_f32_16x16x32_bf16 v[108:111], v[154:157], v[198:201], v[108:111]
	v_mfma_f32_16x16x32_bf16 v[96:99], v[146:149], v[206:209], v[96:99]
	v_mfma_f32_16x16x32_bf16 v[92:95], v[154:157], v[206:209], v[92:95]
	v_mfma_f32_16x16x32_bf16 v[80:83], v[146:149], v[214:217], v[80:83]
	v_mfma_f32_16x16x32_bf16 v[76:79], v[154:157], v[214:217], v[76:79]
	v_mfma_f32_16x16x32_bf16 v[128:131], v[150:153], v[194:197], v[128:131]
	v_mfma_f32_16x16x32_bf16 v[124:127], v[158:161], v[194:197], v[124:127]
	v_mfma_f32_16x16x32_bf16 v[112:115], v[150:153], v[202:205], v[112:115]
	v_mfma_f32_16x16x32_bf16 v[108:111], v[158:161], v[202:205], v[108:111]
	v_mfma_f32_16x16x32_bf16 v[96:99], v[150:153], v[210:213], v[96:99]
	v_mfma_f32_16x16x32_bf16 v[92:95], v[158:161], v[210:213], v[92:95]
	v_mfma_f32_16x16x32_bf16 v[80:83], v[150:153], v[218:221], v[80:83]
	v_mfma_f32_16x16x32_bf16 v[76:79], v[158:161], v[218:221], v[76:79]
	s_setprio 0
	s_setprio 1
	v_mfma_f32_16x16x32_bf16 v[120:123], v[162:165], v[190:193], v[120:123]
	v_mfma_f32_16x16x32_bf16 v[116:119], v[170:173], v[190:193], v[116:119]
	v_mfma_f32_16x16x32_bf16 v[104:107], v[162:165], v[198:201], v[104:107]
	v_mfma_f32_16x16x32_bf16 v[100:103], v[170:173], v[198:201], v[100:103]
	v_mfma_f32_16x16x32_bf16 v[88:91], v[162:165], v[206:209], v[88:91]
	v_mfma_f32_16x16x32_bf16 v[84:87], v[170:173], v[206:209], v[84:87]
	v_mfma_f32_16x16x32_bf16 v[72:75], v[162:165], v[214:217], v[72:75]
	v_mfma_f32_16x16x32_bf16 v[68:71], v[170:173], v[214:217], v[68:71]
	v_mfma_f32_16x16x32_bf16 v[120:123], v[166:169], v[194:197], v[120:123]
	v_mfma_f32_16x16x32_bf16 v[116:119], v[186:189], v[194:197], v[116:119]
	v_mfma_f32_16x16x32_bf16 v[104:107], v[166:169], v[202:205], v[104:107]
	v_mfma_f32_16x16x32_bf16 v[100:103], v[186:189], v[202:205], v[100:103]
	v_mfma_f32_16x16x32_bf16 v[88:91], v[166:169], v[210:213], v[88:91]
	v_mfma_f32_16x16x32_bf16 v[84:87], v[186:189], v[210:213], v[84:87]
	v_mfma_f32_16x16x32_bf16 v[72:75], v[166:169], v[218:221], v[72:75]
	v_mfma_f32_16x16x32_bf16 v[68:71], v[186:189], v[218:221], v[68:71]
	s_setprio 0
	s_barrier
	s_add_i32 s42, s64, s69
	s_mov_b32 m0, s42
	s_nop 0
	global_load_lds_dwordx4 v142, s[48:49]
	s_add_i32 m0, s42, 0x2000
	s_add_u32 s42, s48, 0x40000
	s_addc_u32 s43, s49, 0
	s_add_i32 s64, s65, s69
	global_load_lds_dwordx4 v0, s[48:49]
	s_mov_b32 m0, s64
	s_nop 0
	global_load_lds_dwordx4 v142, s[42:43]
	s_add_i32 m0, s64, 0x2000
	s_nop 0
	global_load_lds_dwordx4 v0, s[42:43]
	ds_read_b128 v[190:193], v132 offset:16384
	ds_read_b128 v[194:197], v132 offset:17408
	ds_read_b128 v[198:201], v132 offset:18432
	ds_read_b128 v[202:205], v132 offset:19456
	ds_read_b128 v[206:209], v132 offset:20480
	ds_read_b128 v[210:213], v132 offset:21504
	ds_read_b128 v[214:217], v132 offset:22528
	ds_read_b128 v[218:221], v132 offset:23552
	s_waitcnt vmcnt(4)
	s_waitcnt lgkmcnt(0)
	s_barrier
	s_setprio 1
	s_waitcnt lgkmcnt(0)
	v_mfma_f32_16x16x32_bf16 v[64:67], v[146:149], v[190:193], v[64:67]
	v_mfma_f32_16x16x32_bf16 v[60:63], v[154:157], v[190:193], v[60:63]
	v_mfma_f32_16x16x32_bf16 v[48:51], v[146:149], v[198:201], v[48:51]
	v_mfma_f32_16x16x32_bf16 v[44:47], v[154:157], v[198:201], v[44:47]
	v_mfma_f32_16x16x32_bf16 v[32:35], v[146:149], v[206:209], v[32:35]
	v_mfma_f32_16x16x32_bf16 v[28:31], v[154:157], v[206:209], v[28:31]
	v_mfma_f32_16x16x32_bf16 v[16:19], v[146:149], v[214:217], v[16:19]
	v_mfma_f32_16x16x32_bf16 v[12:15], v[154:157], v[214:217], v[12:15]
	v_mfma_f32_16x16x32_bf16 v[64:67], v[150:153], v[194:197], v[64:67]
	v_mfma_f32_16x16x32_bf16 v[60:63], v[158:161], v[194:197], v[60:63]
	v_mfma_f32_16x16x32_bf16 v[48:51], v[150:153], v[202:205], v[48:51]
	v_mfma_f32_16x16x32_bf16 v[44:47], v[158:161], v[202:205], v[44:47]
	v_mfma_f32_16x16x32_bf16 v[32:35], v[150:153], v[210:213], v[32:35]
	v_mfma_f32_16x16x32_bf16 v[28:31], v[158:161], v[210:213], v[28:31]
	v_mfma_f32_16x16x32_bf16 v[16:19], v[150:153], v[218:221], v[16:19]
	v_mfma_f32_16x16x32_bf16 v[12:15], v[158:161], v[218:221], v[12:15]
	s_setprio 0
	s_setprio 1
	v_mfma_f32_16x16x32_bf16 v[56:59], v[162:165], v[190:193], v[56:59]
	v_mfma_f32_16x16x32_bf16 v[52:55], v[170:173], v[190:193], v[52:55]
	v_mfma_f32_16x16x32_bf16 v[40:43], v[162:165], v[198:201], v[40:43]
	v_mfma_f32_16x16x32_bf16 v[36:39], v[170:173], v[198:201], v[36:39]
	v_mfma_f32_16x16x32_bf16 v[24:27], v[162:165], v[206:209], v[24:27]
	v_mfma_f32_16x16x32_bf16 v[20:23], v[170:173], v[206:209], v[20:23]
	v_mfma_f32_16x16x32_bf16 v[8:11], v[162:165], v[214:217], v[8:11]
	v_mfma_f32_16x16x32_bf16 v[4:7], v[170:173], v[214:217], v[4:7]
	v_mfma_f32_16x16x32_bf16 v[56:59], v[166:169], v[194:197], v[56:59]
	v_mfma_f32_16x16x32_bf16 v[52:55], v[186:189], v[194:197], v[52:55]
	v_mfma_f32_16x16x32_bf16 v[40:43], v[166:169], v[202:205], v[40:43]
	v_mfma_f32_16x16x32_bf16 v[36:39], v[186:189], v[202:205], v[36:39]
	v_mfma_f32_16x16x32_bf16 v[24:27], v[166:169], v[210:213], v[24:27]
	v_mfma_f32_16x16x32_bf16 v[20:23], v[186:189], v[210:213], v[20:23]
	v_mfma_f32_16x16x32_bf16 v[8:11], v[166:169], v[218:221], v[8:11]
	v_mfma_f32_16x16x32_bf16 v[4:7], v[186:189], v[218:221], v[4:7]
	s_setprio 0
	s_barrier
	s_add_i32 s64, 0, 0x18000
	v_add_u32_e32 v138, s64, v3
	s_add_i32 s65, 0, 0x1c000
	ds_read_b128 v[146:149], v138
	ds_read_b128 v[150:153], v138 offset:1024
	ds_read_b128 v[154:157], v138 offset:2048
	ds_read_b128 v[158:161], v138 offset:3072
	v_add_u32_e32 v138, s65, v3
	ds_read_b128 v[162:165], v138
	ds_read_b128 v[166:169], v138 offset:1024
	ds_read_b128 v[170:173], v138 offset:2048
	ds_read_b128 v[186:189], v138 offset:3072
	s_add_u32 s42, s50, 0x40000
	s_addc_u32 s43, s51, 0
	s_mov_b32 m0, s56
	s_nop 0
	global_load_lds_dwordx4 v144, s[50:51]
	s_mov_b32 m0, s57
	s_nop 0
	global_load_lds_dwordx4 v140, s[50:51]
	s_mov_b32 m0, s58
	s_nop 0
	global_load_lds_dwordx4 v144, s[42:43]
	s_mov_b32 m0, s59
	s_nop 0
	global_load_lds_dwordx4 v140, s[42:43]
	ds_read_b128 v[190:193], v132 offset:32768
	ds_read_b128 v[194:197], v132 offset:33792
	ds_read_b128 v[198:201], v132 offset:34816
	ds_read_b128 v[202:205], v132 offset:35840
	ds_read_b128 v[206:209], v132 offset:36864
	ds_read_b128 v[210:213], v132 offset:37888
	ds_read_b128 v[214:217], v132 offset:38912
	ds_read_b128 v[218:221], v132 offset:39936
	s_waitcnt vmcnt(8)
	s_waitcnt lgkmcnt(0)
	s_barrier
	s_setprio 1
	s_waitcnt lgkmcnt(0)
	v_mfma_f32_16x16x32_bf16 v[128:131], v[146:149], v[190:193], v[128:131]
	v_mfma_f32_16x16x32_bf16 v[124:127], v[154:157], v[190:193], v[124:127]
	v_mfma_f32_16x16x32_bf16 v[112:115], v[146:149], v[198:201], v[112:115]
	v_mfma_f32_16x16x32_bf16 v[108:111], v[154:157], v[198:201], v[108:111]
	v_mfma_f32_16x16x32_bf16 v[96:99], v[146:149], v[206:209], v[96:99]
	v_mfma_f32_16x16x32_bf16 v[92:95], v[154:157], v[206:209], v[92:95]
	v_mfma_f32_16x16x32_bf16 v[80:83], v[146:149], v[214:217], v[80:83]
	v_mfma_f32_16x16x32_bf16 v[76:79], v[154:157], v[214:217], v[76:79]
	v_mfma_f32_16x16x32_bf16 v[128:131], v[150:153], v[194:197], v[128:131]
	v_mfma_f32_16x16x32_bf16 v[124:127], v[158:161], v[194:197], v[124:127]
	v_mfma_f32_16x16x32_bf16 v[112:115], v[150:153], v[202:205], v[112:115]
	v_mfma_f32_16x16x32_bf16 v[108:111], v[158:161], v[202:205], v[108:111]
	v_mfma_f32_16x16x32_bf16 v[96:99], v[150:153], v[210:213], v[96:99]
	v_mfma_f32_16x16x32_bf16 v[92:95], v[158:161], v[210:213], v[92:95]
	v_mfma_f32_16x16x32_bf16 v[80:83], v[150:153], v[218:221], v[80:83]
	v_mfma_f32_16x16x32_bf16 v[76:79], v[158:161], v[218:221], v[76:79]
	s_setprio 0
	s_setprio 1
	v_mfma_f32_16x16x32_bf16 v[120:123], v[162:165], v[190:193], v[120:123]
	v_mfma_f32_16x16x32_bf16 v[116:119], v[170:173], v[190:193], v[116:119]
	v_mfma_f32_16x16x32_bf16 v[104:107], v[162:165], v[198:201], v[104:107]
	v_mfma_f32_16x16x32_bf16 v[100:103], v[170:173], v[198:201], v[100:103]
	v_mfma_f32_16x16x32_bf16 v[88:91], v[162:165], v[206:209], v[88:91]
	v_mfma_f32_16x16x32_bf16 v[84:87], v[170:173], v[206:209], v[84:87]
	v_mfma_f32_16x16x32_bf16 v[72:75], v[162:165], v[214:217], v[72:75]
	v_mfma_f32_16x16x32_bf16 v[68:71], v[170:173], v[214:217], v[68:71]
	v_mfma_f32_16x16x32_bf16 v[120:123], v[166:169], v[194:197], v[120:123]
	v_mfma_f32_16x16x32_bf16 v[116:119], v[186:189], v[194:197], v[116:119]
	v_mfma_f32_16x16x32_bf16 v[104:107], v[166:169], v[202:205], v[104:107]
	v_mfma_f32_16x16x32_bf16 v[100:103], v[186:189], v[202:205], v[100:103]
	v_mfma_f32_16x16x32_bf16 v[88:91], v[166:169], v[210:213], v[88:91]
	v_mfma_f32_16x16x32_bf16 v[84:87], v[186:189], v[210:213], v[84:87]
	v_mfma_f32_16x16x32_bf16 v[72:75], v[166:169], v[218:221], v[72:75]
	v_mfma_f32_16x16x32_bf16 v[68:71], v[186:189], v[218:221], v[68:71]
	s_setprio 0
	s_barrier
	s_add_u32 s42, s48, 0x80
	s_addc_u32 s43, s49, 0
	s_add_i32 s50, s64, s69
	s_mov_b32 m0, s50
	s_nop 0
	global_load_lds_dwordx4 v142, s[42:43]
	s_add_i32 m0, s50, 0x2000
	s_nop 0
	global_load_lds_dwordx4 v0, s[42:43]
	s_add_u32 s42, s48, 0x40080
	s_addc_u32 s43, s49, 0
	s_add_i32 s48, s65, s69
	s_mov_b32 m0, s48
	s_nop 0
	global_load_lds_dwordx4 v142, s[42:43]
	s_add_i32 m0, s48, 0x2000
	s_nop 0
	global_load_lds_dwordx4 v0, s[42:43]
	ds_read_b128 v[190:193], v132 offset:49152
	ds_read_b128 v[194:197], v132 offset:50176
	ds_read_b128 v[198:201], v132 offset:51200
	ds_read_b128 v[202:205], v132 offset:52224
	ds_read_b128 v[206:209], v132 offset:53248
	ds_read_b128 v[210:213], v132 offset:54272
	ds_read_b128 v[214:217], v132 offset:55296
	ds_read_b128 v[218:221], v132 offset:56320
	s_waitcnt vmcnt(4)
	s_waitcnt lgkmcnt(0)
	s_barrier
	s_setprio 1
	s_waitcnt lgkmcnt(0)
	v_mfma_f32_16x16x32_bf16 v[64:67], v[146:149], v[190:193], v[64:67]
	v_mfma_f32_16x16x32_bf16 v[60:63], v[154:157], v[190:193], v[60:63]
	v_mfma_f32_16x16x32_bf16 v[48:51], v[146:149], v[198:201], v[48:51]
	v_mfma_f32_16x16x32_bf16 v[44:47], v[154:157], v[198:201], v[44:47]
	v_mfma_f32_16x16x32_bf16 v[32:35], v[146:149], v[206:209], v[32:35]
	v_mfma_f32_16x16x32_bf16 v[28:31], v[154:157], v[206:209], v[28:31]
	v_mfma_f32_16x16x32_bf16 v[16:19], v[146:149], v[214:217], v[16:19]
	v_mfma_f32_16x16x32_bf16 v[12:15], v[154:157], v[214:217], v[12:15]
	v_mfma_f32_16x16x32_bf16 v[64:67], v[150:153], v[194:197], v[64:67]
	v_mfma_f32_16x16x32_bf16 v[60:63], v[158:161], v[194:197], v[60:63]
	v_mfma_f32_16x16x32_bf16 v[48:51], v[150:153], v[202:205], v[48:51]
	v_mfma_f32_16x16x32_bf16 v[44:47], v[158:161], v[202:205], v[44:47]
	v_mfma_f32_16x16x32_bf16 v[32:35], v[150:153], v[210:213], v[32:35]
	v_mfma_f32_16x16x32_bf16 v[28:31], v[158:161], v[210:213], v[28:31]
	v_mfma_f32_16x16x32_bf16 v[16:19], v[150:153], v[218:221], v[16:19]
	v_mfma_f32_16x16x32_bf16 v[12:15], v[158:161], v[218:221], v[12:15]
	s_setprio 0
	s_setprio 1
	v_mfma_f32_16x16x32_bf16 v[56:59], v[162:165], v[190:193], v[56:59]
	v_mfma_f32_16x16x32_bf16 v[52:55], v[170:173], v[190:193], v[52:55]
	v_mfma_f32_16x16x32_bf16 v[40:43], v[162:165], v[198:201], v[40:43]
	v_mfma_f32_16x16x32_bf16 v[36:39], v[170:173], v[198:201], v[36:39]
	v_mfma_f32_16x16x32_bf16 v[24:27], v[162:165], v[206:209], v[24:27]
	v_mfma_f32_16x16x32_bf16 v[20:23], v[170:173], v[206:209], v[20:23]
	v_mfma_f32_16x16x32_bf16 v[8:11], v[162:165], v[214:217], v[8:11]
	v_mfma_f32_16x16x32_bf16 v[4:7], v[170:173], v[214:217], v[4:7]
	v_mfma_f32_16x16x32_bf16 v[56:59], v[166:169], v[194:197], v[56:59]
	v_mfma_f32_16x16x32_bf16 v[52:55], v[186:189], v[194:197], v[52:55]
	v_mfma_f32_16x16x32_bf16 v[40:43], v[166:169], v[202:205], v[40:43]
	v_mfma_f32_16x16x32_bf16 v[36:39], v[186:189], v[202:205], v[36:39]
	v_mfma_f32_16x16x32_bf16 v[24:27], v[166:169], v[210:213], v[24:27]
	v_mfma_f32_16x16x32_bf16 v[20:23], v[186:189], v[210:213], v[20:23]
	v_mfma_f32_16x16x32_bf16 v[8:11], v[166:169], v[218:221], v[8:11]
	v_mfma_f32_16x16x32_bf16 v[4:7], v[186:189], v[218:221], v[4:7]
	s_setprio 0
	s_barrier
	s_add_i32 s63, s63, 2
	s_add_u32 s28, s28, 0x100
	s_addc_u32 s29, s29, 0
	s_cmp_gt_u32 s63, 13
	s_mov_b64 s[42:43], s[44:45]
	s_cbranch_scc0 .LBB0_500
	s_and_b64 vcc, exec, s[14:15]
	s_cbranch_vccz .LBB0_503
	s_barrier
.LBB0_503:
	v_mov_b32_e32 v139, v174
	s_lshl_b32 s5, s9, 8
	s_add_i32 s5, s5, s70
	v_and_or_b32 v138, v139, 15, s5
	s_lshl_b32 s5, s8, 7
	v_ashrrev_i32_e32 v139, 1, v139
	s_or_b32 s5, s5, s71
	v_and_b32_e32 v139, -8, v139
	v_add_u32_e32 v148, s5, v139
	v_ashrrev_i32_e32 v149, 31, v148
	v_mov_b64_e32 v[146:147], s[0:1]
	v_ashrrev_i32_e32 v139, 31, v138
	v_mad_i64_i32 v[150:151], s[8:9], v138, s73, v[146:147]
	v_lshlrev_b64 v[148:149], 1, v[148:149]
	v_lshl_add_u64 v[152:153], v[150:151], 0, v[148:149]
	v_lshl_add_u64 v[150:151], v[138:139], 2, s[2:3]
	global_load_dword v206, v[150:151], off
	global_load_dword v208, v[150:151], off offset:64
	global_load_dword v210, v[150:151], off offset:128
	global_load_dword v212, v[150:151], off offset:192
	global_load_dword v214, v[150:151], off offset:512
	global_load_dword v216, v[150:151], off offset:576
	global_load_dword v218, v[150:151], off offset:640
	global_load_dword v220, v[150:151], off offset:704
	s_mov_b64 s[42:43], -1
	s_andn2_b64 vcc, exec, s[40:41]
	v_mov_b32_e32 v154, 0xbfb8aa3b
	v_mov_b32_e32 v155, 0xbfb8aa3b
	v_mov_b32_e32 v156, 1.0
	v_mov_b32_e32 v157, 1.0
	v_mov_b32_e32 v159, 0
	s_waitcnt vmcnt(0)
	v_pk_mul_f32 v[128:129], v[128:129], v[206:207] op_sel_hi:[1,0]
	v_pk_mul_f32 v[130:131], v[130:131], v[206:207] op_sel_hi:[1,0]
	v_pk_mul_f32 v[124:125], v[124:125], v[206:207] op_sel_hi:[1,0]
	v_pk_mul_f32 v[126:127], v[126:127], v[206:207] op_sel_hi:[1,0]
	v_pk_mul_f32 v[162:163], v[128:129], v[154:155]
	v_pk_mul_f32 v[164:165], v[130:131], v[154:155]
	v_pk_mul_f32 v[166:167], v[124:125], v[154:155]
	v_pk_mul_f32 v[168:169], v[126:127], v[154:155]
	v_exp_f32_e32 v162, v162
	v_exp_f32_e32 v163, v163
	v_exp_f32_e32 v164, v164
	v_exp_f32_e32 v165, v165
	v_exp_f32_e32 v166, v166
	v_exp_f32_e32 v167, v167
	v_exp_f32_e32 v168, v168
	v_exp_f32_e32 v169, v169
	v_pk_mul_f32 v[120:121], v[120:121], v[206:207] op_sel_hi:[1,0]
	v_pk_mul_f32 v[122:123], v[122:123], v[206:207] op_sel_hi:[1,0]
	v_pk_mul_f32 v[116:117], v[116:117], v[206:207] op_sel_hi:[1,0]
	v_pk_mul_f32 v[118:119], v[118:119], v[206:207] op_sel_hi:[1,0]
	v_pk_add_f32 v[162:163], v[162:163], v[156:157]
	v_pk_add_f32 v[164:165], v[164:165], v[156:157]
	v_pk_add_f32 v[166:167], v[166:167], v[156:157]
	v_pk_add_f32 v[168:169], v[168:169], v[156:157]
	v_rcp_f32_e32 v162, v162
	v_rcp_f32_e32 v163, v163
	v_rcp_f32_e32 v164, v164
	v_rcp_f32_e32 v165, v165
	v_rcp_f32_e32 v166, v166
	v_rcp_f32_e32 v167, v167
	v_rcp_f32_e32 v168, v168
	v_rcp_f32_e32 v169, v169
	v_pk_mul_f32 v[128:129], v[128:129], v[120:121]
	v_pk_mul_f32 v[130:131], v[130:131], v[122:123]
	v_pk_mul_f32 v[124:125], v[124:125], v[116:117]
	v_pk_mul_f32 v[126:127], v[126:127], v[118:119]
	v_pk_mul_f32 v[128:129], v[128:129], v[162:163]
	v_pk_mul_f32 v[130:131], v[130:131], v[164:165]
	v_pk_mul_f32 v[124:125], v[124:125], v[166:167]
	v_pk_mul_f32 v[126:127], v[126:127], v[168:169]
	v_cvt_pk_bf16_f32 v170, v128, v129
	v_cvt_pk_bf16_f32 v171, v130, v131
	v_cvt_pk_bf16_f32 v172, v124, v125
	v_cvt_pk_bf16_f32 v173, v126, v127
	global_store_dwordx4 v[152:153], v[170:173], off
	v_pk_mul_f32 v[112:113], v[112:113], v[208:209] op_sel_hi:[1,0]
	v_pk_mul_f32 v[114:115], v[114:115], v[208:209] op_sel_hi:[1,0]
	v_pk_mul_f32 v[108:109], v[108:109], v[208:209] op_sel_hi:[1,0]
	v_pk_mul_f32 v[110:111], v[110:111], v[208:209] op_sel_hi:[1,0]
	v_pk_mul_f32 v[162:163], v[112:113], v[154:155]
	v_pk_mul_f32 v[164:165], v[114:115], v[154:155]
	v_pk_mul_f32 v[166:167], v[108:109], v[154:155]
	v_pk_mul_f32 v[168:169], v[110:111], v[154:155]
	v_exp_f32_e32 v162, v162
	v_exp_f32_e32 v163, v163
	v_exp_f32_e32 v164, v164
	v_exp_f32_e32 v165, v165
	v_exp_f32_e32 v166, v166
	v_exp_f32_e32 v167, v167
	v_exp_f32_e32 v168, v168
	v_exp_f32_e32 v169, v169
	v_pk_mul_f32 v[104:105], v[104:105], v[208:209] op_sel_hi:[1,0]
	v_pk_mul_f32 v[106:107], v[106:107], v[208:209] op_sel_hi:[1,0]
	v_pk_mul_f32 v[100:101], v[100:101], v[208:209] op_sel_hi:[1,0]
	v_pk_mul_f32 v[102:103], v[102:103], v[208:209] op_sel_hi:[1,0]
	v_pk_add_f32 v[162:163], v[162:163], v[156:157]
	v_pk_add_f32 v[164:165], v[164:165], v[156:157]
	v_pk_add_f32 v[166:167], v[166:167], v[156:157]
	v_pk_add_f32 v[168:169], v[168:169], v[156:157]
	v_rcp_f32_e32 v162, v162
	v_rcp_f32_e32 v163, v163
	v_rcp_f32_e32 v164, v164
	v_rcp_f32_e32 v165, v165
	v_rcp_f32_e32 v166, v166
	v_rcp_f32_e32 v167, v167
	v_rcp_f32_e32 v168, v168
	v_rcp_f32_e32 v169, v169
	v_pk_mul_f32 v[112:113], v[112:113], v[104:105]
	v_pk_mul_f32 v[114:115], v[114:115], v[106:107]
	v_pk_mul_f32 v[108:109], v[108:109], v[100:101]
	v_pk_mul_f32 v[110:111], v[110:111], v[102:103]
	v_pk_mul_f32 v[112:113], v[112:113], v[162:163]
	v_pk_mul_f32 v[114:115], v[114:115], v[164:165]
	v_pk_mul_f32 v[108:109], v[108:109], v[166:167]
	v_pk_mul_f32 v[110:111], v[110:111], v[168:169]
	v_cvt_pk_bf16_f32 v186, v112, v113
	v_cvt_pk_bf16_f32 v187, v114, v115
	v_cvt_pk_bf16_f32 v188, v108, v109
	v_cvt_pk_bf16_f32 v189, v110, v111
	v_mov_b32_e32 v158, 0x16000
	v_lshl_add_u64 v[160:161], v[152:153], 0, v[158:159]
	global_store_dwordx4 v[160:161], v[186:189], off
	v_pk_mul_f32 v[96:97], v[96:97], v[210:211] op_sel_hi:[1,0]
	v_pk_mul_f32 v[98:99], v[98:99], v[210:211] op_sel_hi:[1,0]
	v_pk_mul_f32 v[92:93], v[92:93], v[210:211] op_sel_hi:[1,0]
	v_pk_mul_f32 v[94:95], v[94:95], v[210:211] op_sel_hi:[1,0]
	v_pk_mul_f32 v[162:163], v[96:97], v[154:155]
	v_pk_mul_f32 v[164:165], v[98:99], v[154:155]
	v_pk_mul_f32 v[166:167], v[92:93], v[154:155]
	v_pk_mul_f32 v[168:169], v[94:95], v[154:155]
	v_exp_f32_e32 v162, v162
	v_exp_f32_e32 v163, v163
	v_exp_f32_e32 v164, v164
	v_exp_f32_e32 v165, v165
	v_exp_f32_e32 v166, v166
	v_exp_f32_e32 v167, v167
	v_exp_f32_e32 v168, v168
	v_exp_f32_e32 v169, v169
	v_pk_mul_f32 v[88:89], v[88:89], v[210:211] op_sel_hi:[1,0]
	v_pk_mul_f32 v[90:91], v[90:91], v[210:211] op_sel_hi:[1,0]
	v_pk_mul_f32 v[84:85], v[84:85], v[210:211] op_sel_hi:[1,0]
	v_pk_mul_f32 v[86:87], v[86:87], v[210:211] op_sel_hi:[1,0]
	v_pk_add_f32 v[162:163], v[162:163], v[156:157]
	v_pk_add_f32 v[164:165], v[164:165], v[156:157]
	v_pk_add_f32 v[166:167], v[166:167], v[156:157]
	v_pk_add_f32 v[168:169], v[168:169], v[156:157]
	v_rcp_f32_e32 v162, v162
	v_rcp_f32_e32 v163, v163
	v_rcp_f32_e32 v164, v164
	v_rcp_f32_e32 v165, v165
	v_rcp_f32_e32 v166, v166
	v_rcp_f32_e32 v167, v167
	v_rcp_f32_e32 v168, v168
	v_rcp_f32_e32 v169, v169
	v_pk_mul_f32 v[96:97], v[96:97], v[88:89]
	v_pk_mul_f32 v[98:99], v[98:99], v[90:91]
	v_pk_mul_f32 v[92:93], v[92:93], v[84:85]
	v_pk_mul_f32 v[94:95], v[94:95], v[86:87]
	v_pk_mul_f32 v[96:97], v[96:97], v[162:163]
	v_pk_mul_f32 v[98:99], v[98:99], v[164:165]
	v_pk_mul_f32 v[92:93], v[92:93], v[166:167]
	v_pk_mul_f32 v[94:95], v[94:95], v[168:169]
	v_cvt_pk_bf16_f32 v170, v96, v97
	v_cvt_pk_bf16_f32 v171, v98, v99
	v_cvt_pk_bf16_f32 v172, v92, v93
	v_cvt_pk_bf16_f32 v173, v94, v95
	v_mov_b32_e32 v158, 0x2c000
	v_lshl_add_u64 v[160:161], v[152:153], 0, v[158:159]
	global_store_dwordx4 v[160:161], v[170:173], off
	v_pk_mul_f32 v[80:81], v[80:81], v[212:213] op_sel_hi:[1,0]
	v_pk_mul_f32 v[82:83], v[82:83], v[212:213] op_sel_hi:[1,0]
	v_pk_mul_f32 v[76:77], v[76:77], v[212:213] op_sel_hi:[1,0]
	v_pk_mul_f32 v[78:79], v[78:79], v[212:213] op_sel_hi:[1,0]
	v_pk_mul_f32 v[162:163], v[80:81], v[154:155]
	v_pk_mul_f32 v[164:165], v[82:83], v[154:155]
	v_pk_mul_f32 v[166:167], v[76:77], v[154:155]
	v_pk_mul_f32 v[168:169], v[78:79], v[154:155]
	v_exp_f32_e32 v162, v162
	v_exp_f32_e32 v163, v163
	v_exp_f32_e32 v164, v164
	v_exp_f32_e32 v165, v165
	v_exp_f32_e32 v166, v166
	v_exp_f32_e32 v167, v167
	v_exp_f32_e32 v168, v168
	v_exp_f32_e32 v169, v169
	v_pk_mul_f32 v[72:73], v[72:73], v[212:213] op_sel_hi:[1,0]
	v_pk_mul_f32 v[74:75], v[74:75], v[212:213] op_sel_hi:[1,0]
	v_pk_mul_f32 v[68:69], v[68:69], v[212:213] op_sel_hi:[1,0]
	v_pk_mul_f32 v[70:71], v[70:71], v[212:213] op_sel_hi:[1,0]
	v_pk_add_f32 v[162:163], v[162:163], v[156:157]
	v_pk_add_f32 v[164:165], v[164:165], v[156:157]
	v_pk_add_f32 v[166:167], v[166:167], v[156:157]
	v_pk_add_f32 v[168:169], v[168:169], v[156:157]
	v_rcp_f32_e32 v162, v162
	v_rcp_f32_e32 v163, v163
	v_rcp_f32_e32 v164, v164
	v_rcp_f32_e32 v165, v165
	v_rcp_f32_e32 v166, v166
	v_rcp_f32_e32 v167, v167
	v_rcp_f32_e32 v168, v168
	v_rcp_f32_e32 v169, v169
	v_pk_mul_f32 v[80:81], v[80:81], v[72:73]
	v_pk_mul_f32 v[82:83], v[82:83], v[74:75]
	v_pk_mul_f32 v[76:77], v[76:77], v[68:69]
	v_pk_mul_f32 v[78:79], v[78:79], v[70:71]
	v_pk_mul_f32 v[80:81], v[80:81], v[162:163]
	v_pk_mul_f32 v[82:83], v[82:83], v[164:165]
	v_pk_mul_f32 v[76:77], v[76:77], v[166:167]
	v_pk_mul_f32 v[78:79], v[78:79], v[168:169]
	v_cvt_pk_bf16_f32 v186, v80, v81
	v_cvt_pk_bf16_f32 v187, v82, v83
	v_cvt_pk_bf16_f32 v188, v76, v77
	v_cvt_pk_bf16_f32 v189, v78, v79
	v_mov_b32_e32 v158, 0x42000
	v_lshl_add_u64 v[160:161], v[152:153], 0, v[158:159]
	global_store_dwordx4 v[160:161], v[186:189], off
	v_pk_mul_f32 v[64:65], v[64:65], v[214:215] op_sel_hi:[1,0]
	v_pk_mul_f32 v[66:67], v[66:67], v[214:215] op_sel_hi:[1,0]
	v_pk_mul_f32 v[60:61], v[60:61], v[214:215] op_sel_hi:[1,0]
	v_pk_mul_f32 v[62:63], v[62:63], v[214:215] op_sel_hi:[1,0]
	v_pk_mul_f32 v[162:163], v[64:65], v[154:155]
	v_pk_mul_f32 v[164:165], v[66:67], v[154:155]
	v_pk_mul_f32 v[166:167], v[60:61], v[154:155]
	v_pk_mul_f32 v[168:169], v[62:63], v[154:155]
	v_exp_f32_e32 v162, v162
	v_exp_f32_e32 v163, v163
	v_exp_f32_e32 v164, v164
	v_exp_f32_e32 v165, v165
	v_exp_f32_e32 v166, v166
	v_exp_f32_e32 v167, v167
	v_exp_f32_e32 v168, v168
	v_exp_f32_e32 v169, v169
	v_pk_mul_f32 v[56:57], v[56:57], v[214:215] op_sel_hi:[1,0]
	v_pk_mul_f32 v[58:59], v[58:59], v[214:215] op_sel_hi:[1,0]
	v_pk_mul_f32 v[52:53], v[52:53], v[214:215] op_sel_hi:[1,0]
	v_pk_mul_f32 v[54:55], v[54:55], v[214:215] op_sel_hi:[1,0]
	v_pk_add_f32 v[162:163], v[162:163], v[156:157]
	v_pk_add_f32 v[164:165], v[164:165], v[156:157]
	v_pk_add_f32 v[166:167], v[166:167], v[156:157]
	v_pk_add_f32 v[168:169], v[168:169], v[156:157]
	v_rcp_f32_e32 v162, v162
	v_rcp_f32_e32 v163, v163
	v_rcp_f32_e32 v164, v164
	v_rcp_f32_e32 v165, v165
	v_rcp_f32_e32 v166, v166
	v_rcp_f32_e32 v167, v167
	v_rcp_f32_e32 v168, v168
	v_rcp_f32_e32 v169, v169
	v_pk_mul_f32 v[64:65], v[64:65], v[56:57]
	v_pk_mul_f32 v[66:67], v[66:67], v[58:59]
	v_pk_mul_f32 v[60:61], v[60:61], v[52:53]
	v_pk_mul_f32 v[62:63], v[62:63], v[54:55]
	v_pk_mul_f32 v[64:65], v[64:65], v[162:163]
	v_pk_mul_f32 v[66:67], v[66:67], v[164:165]
	v_pk_mul_f32 v[60:61], v[60:61], v[166:167]
	v_pk_mul_f32 v[62:63], v[62:63], v[168:169]
	v_cvt_pk_bf16_f32 v170, v64, v65
	v_cvt_pk_bf16_f32 v171, v66, v67
	v_cvt_pk_bf16_f32 v172, v60, v61
	v_cvt_pk_bf16_f32 v173, v62, v63
	v_mov_b32_e32 v158, 0xb0000
	v_lshl_add_u64 v[160:161], v[152:153], 0, v[158:159]
	global_store_dwordx4 v[160:161], v[170:173], off
	v_pk_mul_f32 v[48:49], v[48:49], v[216:217] op_sel_hi:[1,0]
	v_pk_mul_f32 v[50:51], v[50:51], v[216:217] op_sel_hi:[1,0]
	v_pk_mul_f32 v[44:45], v[44:45], v[216:217] op_sel_hi:[1,0]
	v_pk_mul_f32 v[46:47], v[46:47], v[216:217] op_sel_hi:[1,0]
	v_pk_mul_f32 v[162:163], v[48:49], v[154:155]
	v_pk_mul_f32 v[164:165], v[50:51], v[154:155]
	v_pk_mul_f32 v[166:167], v[44:45], v[154:155]
	v_pk_mul_f32 v[168:169], v[46:47], v[154:155]
	v_exp_f32_e32 v162, v162
	v_exp_f32_e32 v163, v163
	v_exp_f32_e32 v164, v164
	v_exp_f32_e32 v165, v165
	v_exp_f32_e32 v166, v166
	v_exp_f32_e32 v167, v167
	v_exp_f32_e32 v168, v168
	v_exp_f32_e32 v169, v169
	v_pk_mul_f32 v[40:41], v[40:41], v[216:217] op_sel_hi:[1,0]
	v_pk_mul_f32 v[42:43], v[42:43], v[216:217] op_sel_hi:[1,0]
	v_pk_mul_f32 v[36:37], v[36:37], v[216:217] op_sel_hi:[1,0]
	v_pk_mul_f32 v[38:39], v[38:39], v[216:217] op_sel_hi:[1,0]
	v_pk_add_f32 v[162:163], v[162:163], v[156:157]
	v_pk_add_f32 v[164:165], v[164:165], v[156:157]
	v_pk_add_f32 v[166:167], v[166:167], v[156:157]
	v_pk_add_f32 v[168:169], v[168:169], v[156:157]
	v_rcp_f32_e32 v162, v162
	v_rcp_f32_e32 v163, v163
	v_rcp_f32_e32 v164, v164
	v_rcp_f32_e32 v165, v165
	v_rcp_f32_e32 v166, v166
	v_rcp_f32_e32 v167, v167
	v_rcp_f32_e32 v168, v168
	v_rcp_f32_e32 v169, v169
	v_pk_mul_f32 v[48:49], v[48:49], v[40:41]
	v_pk_mul_f32 v[50:51], v[50:51], v[42:43]
	v_pk_mul_f32 v[44:45], v[44:45], v[36:37]
	v_pk_mul_f32 v[46:47], v[46:47], v[38:39]
	v_pk_mul_f32 v[48:49], v[48:49], v[162:163]
	v_pk_mul_f32 v[50:51], v[50:51], v[164:165]
	v_pk_mul_f32 v[44:45], v[44:45], v[166:167]
	v_pk_mul_f32 v[46:47], v[46:47], v[168:169]
	v_cvt_pk_bf16_f32 v186, v48, v49
	v_cvt_pk_bf16_f32 v187, v50, v51
	v_cvt_pk_bf16_f32 v188, v44, v45
	v_cvt_pk_bf16_f32 v189, v46, v47
	v_mov_b32_e32 v158, 0xc6000
	v_lshl_add_u64 v[160:161], v[152:153], 0, v[158:159]
	global_store_dwordx4 v[160:161], v[186:189], off
	v_pk_mul_f32 v[32:33], v[32:33], v[218:219] op_sel_hi:[1,0]
	v_pk_mul_f32 v[34:35], v[34:35], v[218:219] op_sel_hi:[1,0]
	v_pk_mul_f32 v[28:29], v[28:29], v[218:219] op_sel_hi:[1,0]
	v_pk_mul_f32 v[30:31], v[30:31], v[218:219] op_sel_hi:[1,0]
	v_pk_mul_f32 v[162:163], v[32:33], v[154:155]
	v_pk_mul_f32 v[164:165], v[34:35], v[154:155]
	v_pk_mul_f32 v[166:167], v[28:29], v[154:155]
	v_pk_mul_f32 v[168:169], v[30:31], v[154:155]
	v_exp_f32_e32 v162, v162
	v_exp_f32_e32 v163, v163
	v_exp_f32_e32 v164, v164
	v_exp_f32_e32 v165, v165
	v_exp_f32_e32 v166, v166
	v_exp_f32_e32 v167, v167
	v_exp_f32_e32 v168, v168
	v_exp_f32_e32 v169, v169
	v_pk_mul_f32 v[24:25], v[24:25], v[218:219] op_sel_hi:[1,0]
	v_pk_mul_f32 v[26:27], v[26:27], v[218:219] op_sel_hi:[1,0]
	v_pk_mul_f32 v[20:21], v[20:21], v[218:219] op_sel_hi:[1,0]
	v_pk_mul_f32 v[22:23], v[22:23], v[218:219] op_sel_hi:[1,0]
	v_pk_add_f32 v[162:163], v[162:163], v[156:157]
	v_pk_add_f32 v[164:165], v[164:165], v[156:157]
	v_pk_add_f32 v[166:167], v[166:167], v[156:157]
	v_pk_add_f32 v[168:169], v[168:169], v[156:157]
	v_rcp_f32_e32 v162, v162
	v_rcp_f32_e32 v163, v163
	v_rcp_f32_e32 v164, v164
	v_rcp_f32_e32 v165, v165
	v_rcp_f32_e32 v166, v166
	v_rcp_f32_e32 v167, v167
	v_rcp_f32_e32 v168, v168
	v_rcp_f32_e32 v169, v169
	v_pk_mul_f32 v[32:33], v[32:33], v[24:25]
	v_pk_mul_f32 v[34:35], v[34:35], v[26:27]
	v_pk_mul_f32 v[28:29], v[28:29], v[20:21]
	v_pk_mul_f32 v[30:31], v[30:31], v[22:23]
	v_pk_mul_f32 v[32:33], v[32:33], v[162:163]
	v_pk_mul_f32 v[34:35], v[34:35], v[164:165]
	v_pk_mul_f32 v[28:29], v[28:29], v[166:167]
	v_pk_mul_f32 v[30:31], v[30:31], v[168:169]
	v_cvt_pk_bf16_f32 v170, v32, v33
	v_cvt_pk_bf16_f32 v171, v34, v35
	v_cvt_pk_bf16_f32 v172, v28, v29
	v_cvt_pk_bf16_f32 v173, v30, v31
	v_mov_b32_e32 v158, 0xdc000
	v_lshl_add_u64 v[160:161], v[152:153], 0, v[158:159]
	global_store_dwordx4 v[160:161], v[170:173], off
	v_pk_mul_f32 v[16:17], v[16:17], v[220:221] op_sel_hi:[1,0]
	v_pk_mul_f32 v[18:19], v[18:19], v[220:221] op_sel_hi:[1,0]
	v_pk_mul_f32 v[12:13], v[12:13], v[220:221] op_sel_hi:[1,0]
	v_pk_mul_f32 v[14:15], v[14:15], v[220:221] op_sel_hi:[1,0]
	v_pk_mul_f32 v[162:163], v[16:17], v[154:155]
	v_pk_mul_f32 v[164:165], v[18:19], v[154:155]
	v_pk_mul_f32 v[166:167], v[12:13], v[154:155]
	v_pk_mul_f32 v[168:169], v[14:15], v[154:155]
	v_exp_f32_e32 v162, v162
	v_exp_f32_e32 v163, v163
	v_exp_f32_e32 v164, v164
	v_exp_f32_e32 v165, v165
	v_exp_f32_e32 v166, v166
	v_exp_f32_e32 v167, v167
	v_exp_f32_e32 v168, v168
	v_exp_f32_e32 v169, v169
	v_pk_mul_f32 v[8:9], v[8:9], v[220:221] op_sel_hi:[1,0]
	v_pk_mul_f32 v[10:11], v[10:11], v[220:221] op_sel_hi:[1,0]
	v_pk_mul_f32 v[4:5], v[4:5], v[220:221] op_sel_hi:[1,0]
	v_pk_mul_f32 v[6:7], v[6:7], v[220:221] op_sel_hi:[1,0]
	v_pk_add_f32 v[162:163], v[162:163], v[156:157]
	v_pk_add_f32 v[164:165], v[164:165], v[156:157]
	v_pk_add_f32 v[166:167], v[166:167], v[156:157]
	v_pk_add_f32 v[168:169], v[168:169], v[156:157]
	v_rcp_f32_e32 v162, v162
	v_rcp_f32_e32 v163, v163
	v_rcp_f32_e32 v164, v164
	v_rcp_f32_e32 v165, v165
	v_rcp_f32_e32 v166, v166
	v_rcp_f32_e32 v167, v167
	v_rcp_f32_e32 v168, v168
	v_rcp_f32_e32 v169, v169
	v_pk_mul_f32 v[16:17], v[16:17], v[8:9]
	v_pk_mul_f32 v[18:19], v[18:19], v[10:11]
	v_pk_mul_f32 v[12:13], v[12:13], v[4:5]
	v_pk_mul_f32 v[14:15], v[14:15], v[6:7]
	v_pk_mul_f32 v[16:17], v[16:17], v[162:163]
	v_pk_mul_f32 v[18:19], v[18:19], v[164:165]
	v_pk_mul_f32 v[12:13], v[12:13], v[166:167]
	v_pk_mul_f32 v[14:15], v[14:15], v[168:169]
	v_cvt_pk_bf16_f32 v186, v16, v17
	v_cvt_pk_bf16_f32 v187, v18, v19
	v_cvt_pk_bf16_f32 v188, v12, v13
	v_cvt_pk_bf16_f32 v189, v14, v15
	v_mov_b32_e32 v158, 0xf2000
	v_lshl_add_u64 v[160:161], v[152:153], 0, v[158:159]
	global_store_dwordx4 v[160:161], v[186:189], off
	s_cbranch_vccnz .LBB0_496
	s_and_b64 vcc, exec, s[38:39]
	s_cbranch_vccnz .LBB0_495
	s_barrier
	s_branch .LBB0_495

	.amdhsa_kernel _Z10hybrid_fwd4Args
		.amdhsa_group_segment_fixed_size 0
		.amdhsa_private_segment_fixed_size 0
		.amdhsa_kernarg_size 416
		.amdhsa_user_sgpr_count 2
		.amdhsa_user_sgpr_dispatch_ptr 0
		.amdhsa_user_sgpr_queue_ptr 0
		.amdhsa_user_sgpr_kernarg_segment_ptr 1
		.amdhsa_user_sgpr_dispatch_id 0
		.amdhsa_user_sgpr_kernarg_preload_length 0
		.amdhsa_user_sgpr_kernarg_preload_offset 0
		.amdhsa_user_sgpr_private_segment_size 0
		.amdhsa_uses_dynamic_stack 0
		.amdhsa_enable_private_segment 0
		.amdhsa_system_sgpr_workgroup_id_x 1
		.amdhsa_system_sgpr_workgroup_id_y 0
		.amdhsa_system_sgpr_workgroup_id_z 0
		.amdhsa_system_sgpr_workgroup_info 0
		.amdhsa_system_vgpr_workitem_id 2
		.amdhsa_next_free_vgpr 251
		.amdhsa_next_free_sgpr 100
		.amdhsa_accum_offset 252
		.amdhsa_reserve_vcc 1
		.amdhsa_float_round_mode_32 0
		.amdhsa_float_round_mode_16_64 0
		.amdhsa_float_denorm_mode_32 3
		.amdhsa_float_denorm_mode_16_64 3
		.amdhsa_dx10_clamp 1
		.amdhsa_ieee_mode 1
		.amdhsa_fp16_overflow 0
		.amdhsa_tg_split 0
		.amdhsa_exception_fp_ieee_invalid_op 0
		.amdhsa_exception_fp_denorm_src 0
		.amdhsa_exception_fp_ieee_div_zero 0
		.amdhsa_exception_fp_ieee_overflow 0
		.amdhsa_exception_fp_ieee_underflow 0
		.amdhsa_exception_fp_ieee_inexact 0
		.amdhsa_exception_int_div_zero 0
	.end_amdhsa_kernel

amdhsa.kernels:
  - .agpr_count:     0
    .args:
      - .offset:         0
        .size:           160
        .value_kind:     by_value
      - .offset:         160
        .size:           4
        .value_kind:     hidden_block_count_x
      - .offset:         164
        .size:           4
        .value_kind:     hidden_block_count_y
      - .offset:         168
        .size:           4
        .value_kind:     hidden_block_count_z
      - .offset:         172
        .size:           2
        .value_kind:     hidden_group_size_x
      - .offset:         174
        .size:           2
        .value_kind:     hidden_group_size_y
      - .offset:         176
        .size:           2
        .value_kind:     hidden_group_size_z
      - .offset:         178
        .size:           2
        .value_kind:     hidden_remainder_x
      - .offset:         180
        .size:           2
        .value_kind:     hidden_remainder_y
      - .offset:         182
        .size:           2
        .value_kind:     hidden_remainder_z
      - .offset:         200
        .size:           8
        .value_kind:     hidden_global_offset_x
      - .offset:         208
        .size:           8
        .value_kind:     hidden_global_offset_y
      - .offset:         216
        .size:           8
        .value_kind:     hidden_global_offset_z
      - .offset:         224
        .size:           2
        .value_kind:     hidden_grid_dims
      - .offset:         248
        .size:           8
        .value_kind:     hidden_multigrid_sync_arg
      - .offset:         280
        .size:           4
        .value_kind:     hidden_dynamic_lds_size
    .group_segment_fixed_size: 0
    .kernarg_segment_align: 8
    .kernarg_segment_size: 416
    .language:       OpenCL C
    .language_version:
      - 2
      - 0
    .max_flat_workgroup_size: 512
    .name:           _Z10hybrid_fwd4Args
    .private_segment_fixed_size: 0
    .sgpr_count:     106
    .sgpr_spill_count: 208
    .symbol:         _Z10hybrid_fwd4Args.kd
    .uniform_work_group_size: 1
    .uses_dynamic_stack: false
    .vgpr_count:     251
    .vgpr_spill_count: 0
    .wavefront_size: 64
